# attention loop: younger half (waves 4-7) raises s_setprio 1 from K-tile iteration 4, reset at tile exit (mid-item priority handoff)
# baseline (speedup 1.0000x reference)
.LBB0_1429:
	v_mov_b32_e32 v4, v252
	s_waitcnt vmcnt(63) expcnt(7) lgkmcnt(15)
	v_readfirstlane_b32 s4, v4
	s_barrier
	s_ashr_i32 s10, s4, 6
	v_and_b32_e32 v173, 63, v4
	s_mul_i32 s5, s10, 0x410
	s_add_i32 s8, s5, 0
	s_add_i32 s11, s18, 0xffb9
	s_and_b32 s9, s11, 0xffff
	s_mul_i32 s2, s9, 0x8889
	s_lshr_b32 s2, s2, 22
	s_lshl_b32 s3, s2, 7
	s_mulk_i32 s2, 0x78
	s_sub_i32 s2, s11, s2
	s_add_i32 s2, s2, 8
	s_and_b32 s2, s2, 0xffff
	s_add_i32 s33, s3, s2
	s_lshr_b32 s2, s33, 7
	s_lshl_b32 s76, s2, 22
	s_lshl_b32 s2, s2, 3
	s_and_b32 s6, s4, 0xffffffc0
	s_add_i32 s2, s10, s2
	s_ashr_i32 s7, s6, 31
	s_ashr_i32 s3, s2, 31
	s_lshl_b64 s[2:3], s[2:3], 20
	s_lshl_b64 s[4:5], s[6:7], 1
	v_lshrrev_b32_e32 v5, 5, v173
	s_add_u32 s30, s95, s4
	v_and_b32_e32 v172, 31, v4
	s_addc_u32 s31, s22, s5
	v_lshlrev_b32_e32 v0, 4, v5
	v_lshl_add_u64 v[2:3], s[30:31], 0, v[0:1]
	v_lshl_or_b32 v0, s33, 6, v172
	v_lshlrev_b64 v[6:7], 10, v[0:1]
	v_or_b32_e32 v162, 32, v0
	v_mov_b32_e32 v163, v1
	v_lshl_add_u64 v[18:19], v[2:3], 0, v[6:7]
	v_lshlrev_b64 v[6:7], 10, v[162:163]
	s_waitcnt lgkmcnt(0)
	s_barrier
	v_lshl_add_u64 v[2:3], v[2:3], 0, v[6:7]
	global_load_dwordx4 v[6:9], v[18:19], off
	global_load_dwordx4 v[10:13], v[18:19], off offset:32
	global_load_dwordx4 v[14:17], v[18:19], off offset:64
	s_nop 0
	global_load_dwordx4 v[18:21], v[18:19], off offset:96
	s_nop 0
	global_load_dwordx4 v[22:25], v[2:3], off
	global_load_dwordx4 v[26:29], v[2:3], off offset:32
	global_load_dwordx4 v[30:33], v[2:3], off offset:64
	global_load_dwordx4 v[34:37], v[2:3], off offset:96
	s_mulk_i32 s10, 0x1bf0
	v_lshlrev_b32_e32 v38, 4, v173
	s_add_i32 s10, s8, s10
	v_and_b32_e32 v3, 32, v4
	v_add_u32_e32 v174, s10, v38
	s_lshl_b32 s10, s11, 16
	v_lshlrev_b32_e32 v2, 10, v172
	v_lshrrev_b32_e32 v3, 1, v3
	v_or3_b32 v2, s10, v2, v3
	s_lshl_b64 s[10:11], s[76:77], 1
	s_add_u32 s10, s10, s4
	v_mov_b32_e32 v3, v1
	s_addc_u32 s11, s11, s5
	v_lshl_add_u64 v[2:3], s[10:11], 0, v[2:3]
	s_mul_hi_u32 s10, s9, 0x2222223
	s_mul_hi_u32 s11, s10, 0x780000
	s_mul_i32 s30, s10, 0x780000
	v_subrev_co_u32_e32 v166, vcc, s30, v2
	v_mov_b32_e32 v2, s11
	s_lshl_b32 s9, s9, 13
	v_subb_co_u32_e32 v167, vcc, v3, v2, vcc
	s_add_u32 s2, s2, s9
	v_lshlrev_b32_e32 v2, 4, v172
	v_lshlrev_b32_e32 v3, 10, v5
	v_or3_b32 v2, v3, v2, s2
	s_addc_u32 s3, s3, 0
	v_or_b32_e32 v3, 0x200, v2
	s_mul_i32 s10, s10, 0xf0000
	v_mov_b32_e32 v4, s3
	v_subrev_co_u32_e32 v168, vcc, s10, v3
	v_lshlrev_b32_e32 v165, 2, v5
	s_nop 0
	v_subbrev_co_u32_e32 v169, vcc, 0, v4, vcc
	v_subrev_co_u32_e32 v170, vcc, s10, v2
	v_sub_u32_e32 v2, v172, v165
	s_nop 0
	v_subbrev_co_u32_e32 v171, vcc, 0, v4, vcc
	v_add_u32_e32 v177, 0x220, v2
	v_mov_b32_e32 v2, v1
	v_mov_b32_e32 v3, v1
	v_mov_b32_e32 v4, v1
	v_mov_b32_e32 v5, v1
	v_mov_b32_e32 v175, 0
	v_mov_b32_e32 v189, 0xf149f2ca
	s_mov_b32 s9, -1
	v_mov_b32_e32 v199, 0xf149f2ca
	v_mov_b32_e32 v176, 0
	v_readfirstlane_b32 s98, v252
	v_mbcnt_lo_u32_b32 v249, -1, 0
	v_mbcnt_hi_u32_b32 v249, -1, v249
	s_lshr_b32 s101, s98, 6
	s_lshl_b32 s98, s101, 13
	s_add_i32 s98, s98, 0x14000
	s_add_i32 s99, s98, 0x1c00
	s_mov_b32 s100, 0x1000
	s_cmp_eq_u32 s101, 7
	s_cselect_b32 s99, 0x3000, s99
	s_cselect_b32 s100, 0xfffe0400, s100
	s_cmp_ge_u32 s101, 4
	s_cselect_b32 s32, 4, 0x63
	v_and_b32_e32 v246, 31, v249
	v_lshrrev_b32_e32 v247, 5, v249
	v_bfe_u32 v248, v249, 1, 3
	v_lshl_add_u32 v250, v246, 7, s98
	v_xor_b32_e32 v241, v247, v248
	v_lshl_add_u32 v241, v241, 4, v250
	v_or_b32_e32 v242, 2, v247
	v_xor_b32_e32 v242, v242, v248
	v_lshl_add_u32 v242, v242, 4, v250
	v_or_b32_e32 v243, 4, v247
	v_xor_b32_e32 v243, v243, v248
	v_lshl_add_u32 v243, v243, 4, v250
	v_or_b32_e32 v244, 6, v247
	v_xor_b32_e32 v244, v244, v248
	v_lshl_add_u32 v244, v244, 4, v250
	v_mov_b32_e32 v245, 0x1000
	v_mov_b32_e32 v251, s100
	v_cmp_lt_u32_e32 vcc, 23, v246
	s_nop 1
	v_cndmask_b32_e32 v245, v245, v251, vcc
	v_add_u32_e32 v248, v244, v245
	v_add_u32_e32 v247, v243, v245
	v_add_u32_e32 v246, v242, v245
	v_add_u32_e32 v245, v241, v245
	v_lshrrev_b32_e32 v250, 3, v249
	v_lshlrev_b32_e32 v250, 10, v250
	v_and_b32_e32 v251, 7, v249
	v_lshrrev_b32_e32 v142, 4, v249
	v_xor_b32_e32 v251, v251, v142
	v_lshl_add_u32 v142, v251, 4, v250
	v_xor_b32_e32 v251, 4, v251
	v_lshl_add_u32 v250, v251, 4, v250
	v_add_u32_e32 v250, 0x2000, v250
	v_readfirstlane_b32 s100, v166
	v_readfirstlane_b32 s101, v167
	s_nop 0
	s_add_u32 s100, s100, s86
	s_addc_u32 s101, s101, s87
	s_add_u32 s100, s100, 0x85ee200
	s_addc_u32 s101, s101, 0
	v_mov_b32_e32 v143, 0
	v_mov_b32_e32 v251, 0
	v_lshl_add_u64 v[166:167], s[100:101], 0, v[142:143]
	v_lshl_add_u64 v[250:251], s[100:101], 0, v[250:251]
	s_mov_b64 s[100:101], 0x4000
	s_mov_b32 m0, s98
	s_nop 0
	global_load_lds_dwordx4 v[166:167], off
	s_add_i32 m0, s98, 0x400
	s_nop 0
	global_load_lds_dwordx4 v[250:251], off
	v_lshl_add_u64 v[142:143], v[166:167], 0, s[100:101]
	s_add_i32 m0, s98, 0x800
	s_nop 0
	global_load_lds_dwordx4 v[142:143], off
	v_lshl_add_u64 v[144:145], v[250:251], 0, s[100:101]
	s_add_i32 m0, s98, 0xc00
	s_nop 0
	global_load_lds_dwordx4 v[144:145], off
	v_lshl_add_u64 v[142:143], v[142:143], 0, s[100:101]
	s_add_i32 m0, s98, 0x1000
	s_nop 0
	global_load_lds_dwordx4 v[142:143], off
	v_lshl_add_u64 v[144:145], v[144:145], 0, s[100:101]
	s_add_i32 m0, s98, 0x1400
	s_nop 0
	global_load_lds_dwordx4 v[144:145], off
	v_lshl_add_u64 v[142:143], v[142:143], 0, s[100:101]
	s_add_i32 m0, s98, 0x1800
	s_nop 0
	global_load_lds_dwordx4 v[142:143], off
	v_lshl_add_u64 v[144:145], v[144:145], 0, s[100:101]
	s_mov_b32 m0, s99
	s_nop 0
	global_load_lds_dwordx4 v[144:145], off
	s_load_dwordx2 s[2:3], s[0:1], 0x40
	s_sub_i32 s10, s98, 0x14000
	s_lshr_b32 s10, s10, 13
	s_mul_i32 s10, s10, 0x101
	v_add_u32_e32 v44, s10, v173
	v_ashrrev_i32_e32 v45, 31, v44
	v_lshl_add_u32 v43, v173, 2, s8
	s_waitcnt lgkmcnt(0)
	v_lshl_add_u64 v[44:45], v[44:45], 2, s[2:3]
	global_load_dword v38, v[44:45], off
	global_load_dword v39, v[44:45], off offset:256
	global_load_dword v40, v[44:45], off offset:512
	global_load_dword v41, v[44:45], off offset:768
	v_cmp_eq_u32_e32 vcc, 0, v173
	s_and_saveexec_b64 s[2:3], vcc
	global_load_dword v42, v[44:45], off offset:1024
	s_waitcnt vmcnt(0)
	v_mul_f32_e32 v42, 0x3fb8aa3b, v42
	ds_write_b32 v43, v42 offset:1024
	ds_write_b32 v43, v42 offset:1028
	ds_write_b32 v43, v42 offset:1032
	ds_write_b32 v43, v42 offset:1036
	s_or_b64 exec, exec, s[2:3]
	v_mul_f32_e32 v38, 0x3fb8aa3b, v38
	v_mul_f32_e32 v39, 0x3fb8aa3b, v39
	v_mul_f32_e32 v40, 0x3fb8aa3b, v40
	v_mul_f32_e32 v41, 0x3fb8aa3b, v41
	ds_write_b32 v43, v38
	ds_write_b32 v43, v39 offset:256
	ds_write_b32 v43, v40 offset:512
	ds_write_b32 v43, v41 offset:768
	s_waitcnt vmcnt(7)
	s_waitcnt vmcnt(6)
	s_waitcnt vmcnt(5)
	s_waitcnt vmcnt(4)
	s_waitcnt vmcnt(3)
	s_waitcnt vmcnt(2)
	s_waitcnt vmcnt(1)
	s_waitcnt vmcnt(0)
	ds_write_b128 v174, v[6:9] offset:16384
	ds_write_b128 v174, v[10:13] offset:17408
	ds_write_b128 v174, v[14:17] offset:18432
	ds_write_b128 v174, v[18:21] offset:19456
	ds_write_b128 v174, v[22:25] offset:20480
	ds_write_b128 v174, v[26:29] offset:21504
	ds_write_b128 v174, v[30:33] offset:22528
	ds_write_b128 v174, v[34:37] offset:23552
	v_mov_b32_e32 v16, v1
	v_mov_b32_e32 v17, v1
	v_mov_b32_e32 v6, v1
	v_mov_b32_e32 v7, v1
	v_mov_b32_e32 v8, v1
	v_mov_b32_e32 v9, v1
	v_mov_b32_e32 v10, v1
	v_mov_b32_e32 v11, v1
	v_mov_b32_e32 v12, v1
	v_mov_b32_e32 v13, v1
	v_mov_b32_e32 v14, v1
	v_mov_b32_e32 v15, v1
	v_mov_b64_e32 v[48:49], v[16:17]
	v_mov_b64_e32 v[32:33], v[16:17]
	v_mov_b64_e32 v[64:65], v[16:17]
	v_mov_b64_e32 v[46:47], v[14:15]
	v_mov_b64_e32 v[44:45], v[12:13]
	v_mov_b64_e32 v[42:43], v[10:11]
	v_mov_b64_e32 v[40:41], v[8:9]
	v_mov_b64_e32 v[38:39], v[6:7]
	v_mov_b64_e32 v[36:37], v[4:5]
	v_mov_b64_e32 v[34:35], v[2:3]
	v_mov_b64_e32 v[30:31], v[14:15]
	v_mov_b64_e32 v[28:29], v[12:13]
	v_mov_b64_e32 v[26:27], v[10:11]
	v_mov_b64_e32 v[24:25], v[8:9]
	v_mov_b64_e32 v[22:23], v[6:7]
	v_mov_b64_e32 v[20:21], v[4:5]
	v_mov_b64_e32 v[18:19], v[2:3]
	v_mov_b64_e32 v[62:63], v[14:15]
	v_mov_b64_e32 v[60:61], v[12:13]
	v_mov_b64_e32 v[58:59], v[10:11]
	v_mov_b64_e32 v[56:57], v[8:9]
	v_mov_b64_e32 v[54:55], v[6:7]
	v_mov_b64_e32 v[52:53], v[4:5]
	v_mov_b64_e32 v[50:51], v[2:3]
	v_mov_b32_e32 v216, 0x3e38aa3b
	v_mov_b32_e32 v217, 0x3e38aa3b
	v_xor_b32_e32 v249, 32, v179
	v_lshlrev_b32_e32 v249, 2, v249
.LBB0_1432:
	s_add_i32 s9, s9, 1
	s_cmp_eq_u32 s9, s32
	s_cbranch_scc0 .Lattn_prio_keep
	s_setprio 1
.Lattn_prio_keep:
	s_waitcnt vmcnt(0)
	ds_read_b128 v[66:69], v241
	ds_read_b128 v[82:85], v242
	ds_read_b128 v[86:89], v243
	ds_read_b128 v[90:93], v244
	ds_read_b128 v[94:97], v245
	ds_read_b128 v[130:133], v246
	ds_read_b128 v[134:137], v247
	ds_read_b128 v[138:141], v248
	ds_read_b128 v[114:117], v174 offset:16384
	ds_read_b128 v[142:145], v174 offset:17408
	ds_read_b128 v[154:157], v174 offset:20480
	ds_read_b128 v[158:161], v174 offset:21504
	s_waitcnt lgkmcnt(3)
	v_mfma_f32_32x32x16_bf16 v[98:113], v[66:69], v[114:117], 0
	ds_read_b128 v[146:149], v174 offset:18432
	ds_read_b128 v[150:153], v174 offset:19456
	ds_read_b128 v[190:193], v174 offset:22528
	ds_read_b128 v[194:197], v174 offset:23552
	s_waitcnt lgkmcnt(5)
	v_mfma_f32_32x32x16_bf16 v[66:81], v[66:69], v[154:157], 0
	v_mfma_f32_32x32x16_bf16 v[98:113], v[82:85], v[142:145], v[98:113]
	s_waitcnt lgkmcnt(4)
	v_mfma_f32_32x32x16_bf16 v[66:81], v[82:85], v[158:161], v[66:81]
	s_waitcnt lgkmcnt(3)
	v_mfma_f32_32x32x16_bf16 v[98:113], v[86:89], v[146:149], v[98:113]
	s_waitcnt lgkmcnt(1)
	v_mfma_f32_32x32x16_bf16 v[66:81], v[86:89], v[190:193], v[66:81]
	v_mfma_f32_32x32x16_bf16 v[98:113], v[90:93], v[150:153], v[98:113]
	s_waitcnt lgkmcnt(0)
	v_mfma_f32_32x32x16_bf16 v[66:81], v[90:93], v[194:197], v[66:81]
	v_mfma_f32_32x32x16_bf16 v[114:129], v[94:97], v[114:117], 0
	v_mfma_f32_32x32x16_bf16 v[82:97], v[94:97], v[154:157], 0
	v_mfma_f32_32x32x16_bf16 v[114:129], v[130:133], v[142:145], v[114:129]
	v_mfma_f32_32x32x16_bf16 v[82:97], v[130:133], v[158:161], v[82:97]
	v_mfma_f32_32x32x16_bf16 v[114:129], v[134:137], v[146:149], v[114:129]
	v_mfma_f32_32x32x16_bf16 v[82:97], v[134:137], v[190:193], v[82:97]
	v_mfma_f32_32x32x16_bf16 v[114:129], v[138:141], v[150:153], v[114:129]
	v_mfma_f32_32x32x16_bf16 v[82:97], v[138:141], v[194:197], v[82:97]
	s_cmp_eq_u32 s9, 8
	s_cbranch_scc1 .Lattn_nopf
	v_lshl_add_u64 v[166:167], v[166:167], 0, s[34:35]
	v_lshl_add_u64 v[250:251], v[250:251], 0, s[34:35]
	s_mov_b32 m0, s98
	s_nop 0
	global_load_lds_dwordx4 v[166:167], off
	s_add_i32 m0, s98, 0x400
	s_nop 0
	global_load_lds_dwordx4 v[250:251], off
	v_lshl_add_u64 v[142:143], v[166:167], 0, s[100:101]
	s_add_i32 m0, s98, 0x800
	s_nop 0
	global_load_lds_dwordx4 v[142:143], off
	v_lshl_add_u64 v[144:145], v[250:251], 0, s[100:101]
	s_add_i32 m0, s98, 0xc00
	s_nop 0
	global_load_lds_dwordx4 v[144:145], off
	v_lshl_add_u64 v[142:143], v[142:143], 0, s[100:101]
	s_add_i32 m0, s98, 0x1000
	s_nop 0
	global_load_lds_dwordx4 v[142:143], off
	v_lshl_add_u64 v[144:145], v[144:145], 0, s[100:101]
	s_add_i32 m0, s98, 0x1400
	s_nop 0
	global_load_lds_dwordx4 v[144:145], off
	v_lshl_add_u64 v[142:143], v[142:143], 0, s[100:101]
	s_add_i32 m0, s98, 0x1800
	s_nop 0
	global_load_lds_dwordx4 v[142:143], off
	v_lshl_add_u64 v[144:145], v[144:145], 0, s[100:101]
	s_mov_b32 m0, s99
	s_nop 0
	global_load_lds_dwordx4 v[144:145], off

.LBB0_1566:
	s_setprio 0
	v_div_scale_f32 v67, s[2:3], v66, v66, 1.0
	v_rcp_f32_e32 v68, v67
	v_div_scale_f32 v69, vcc, 1.0, v66, 1.0
	s_lshl_b32 s2, s6, 2
	v_fma_f32 v70, -v67, v68, 1.0
	v_fmac_f32_e32 v68, v70, v68
	v_mul_f32_e32 v70, v69, v68
	v_fma_f32 v71, -v67, v70, v69
	v_fmac_f32_e32 v70, v71, v68
	v_fma_f32 v67, -v67, v70, v69
	v_div_fmas_f32 v67, v67, v68, v70
	v_div_fixup_f32 v68, v67, v66, 1.0
	v_pk_mul_f32 v[110:111], v[68:69], v[50:51] op_sel_hi:[0,1]
	v_pk_mul_f32 v[50:51], v[110:111], v[110:111]
	v_pk_mul_f32 v[112:113], v[68:69], v[52:53] op_sel_hi:[0,1]
	v_pk_mul_f32 v[52:53], v[112:113], v[112:113]
	v_add_f32_e32 v50, v50, v51
	v_pk_mul_f32 v[108:109], v[68:69], v[54:55] op_sel_hi:[0,1]
	v_add_f32_e32 v50, v52, v50
	v_pk_mul_f32 v[54:55], v[108:109], v[108:109]
	v_add_f32_e32 v50, v53, v50
	v_pk_mul_f32 v[106:107], v[68:69], v[56:57] op_sel_hi:[0,1]
	v_add_f32_e32 v50, v54, v50
	v_pk_mul_f32 v[56:57], v[106:107], v[106:107]
	v_add_f32_e32 v50, v55, v50
	v_pk_mul_f32 v[104:105], v[68:69], v[58:59] op_sel_hi:[0,1]
	v_add_f32_e32 v50, v56, v50
	v_pk_mul_f32 v[58:59], v[104:105], v[104:105]
	v_add_f32_e32 v50, v57, v50
	v_pk_mul_f32 v[102:103], v[68:69], v[60:61] op_sel_hi:[0,1]
	v_add_f32_e32 v50, v58, v50
	v_pk_mul_f32 v[60:61], v[102:103], v[102:103]
	v_add_f32_e32 v50, v59, v50
	v_pk_mul_f32 v[84:85], v[68:69], v[62:63] op_sel_hi:[0,1]
	v_add_f32_e32 v50, v60, v50
	v_pk_mul_f32 v[62:63], v[84:85], v[84:85]
	v_add_f32_e32 v50, v61, v50
	v_pk_mul_f32 v[82:83], v[68:69], v[64:65] op_sel_hi:[0,1]
	v_add_f32_e32 v50, v62, v50
	v_pk_mul_f32 v[64:65], v[82:83], v[82:83]
	v_add_f32_e32 v50, v63, v50
	v_pk_mul_f32 v[80:81], v[68:69], v[34:35] op_sel_hi:[0,1]
	v_add_f32_e32 v50, v64, v50
	v_pk_mul_f32 v[34:35], v[80:81], v[80:81]
	v_add_f32_e32 v50, v65, v50
	v_pk_mul_f32 v[78:79], v[68:69], v[36:37] op_sel_hi:[0,1]
	v_add_f32_e32 v34, v34, v50
	v_pk_mul_f32 v[36:37], v[78:79], v[78:79]
	v_add_f32_e32 v34, v35, v34
	v_pk_mul_f32 v[76:77], v[68:69], v[38:39] op_sel_hi:[0,1]
	v_add_f32_e32 v34, v36, v34
	v_pk_mul_f32 v[38:39], v[76:77], v[76:77]
	v_add_f32_e32 v34, v37, v34
	v_pk_mul_f32 v[74:75], v[68:69], v[40:41] op_sel_hi:[0,1]
	v_add_f32_e32 v34, v38, v34
	v_pk_mul_f32 v[40:41], v[74:75], v[74:75]
	v_add_f32_e32 v34, v39, v34
	v_pk_mul_f32 v[72:73], v[68:69], v[42:43] op_sel_hi:[0,1]
	v_add_f32_e32 v34, v40, v34
	v_pk_mul_f32 v[42:43], v[72:73], v[72:73]
	v_add_f32_e32 v34, v41, v34
	v_pk_mul_f32 v[70:71], v[68:69], v[44:45] op_sel_hi:[0,1]
	v_add_f32_e32 v34, v42, v34
	v_pk_mul_f32 v[44:45], v[70:71], v[70:71]
	v_add_f32_e32 v34, v43, v34
	v_pk_mul_f32 v[66:67], v[68:69], v[46:47] op_sel_hi:[0,1]
	v_add_f32_e32 v34, v44, v34
	v_pk_mul_f32 v[46:47], v[66:67], v[66:67]
	v_add_f32_e32 v34, v45, v34
	v_pk_mul_f32 v[68:69], v[68:69], v[48:49] op_sel_hi:[0,1]
	v_add_f32_e32 v34, v46, v34
	v_pk_mul_f32 v[48:49], v[68:69], v[68:69]
	v_add_f32_e32 v34, v47, v34
	v_add_f32_e32 v34, v48, v34
	v_add_f32_e32 v34, v49, v34
	ds_bpermute_b32 v35, v99, v34
	s_add_i32 s2, s2, 0
	v_cmp_gt_u32_e64 s[40:41], 32, v173
	v_lshl_add_u32 v87, v172, 2, s2
	s_and_saveexec_b64 s[2:3], s[40:41]
	s_cbranch_execz .LBB0_1568
	s_waitcnt lgkmcnt(0)
	v_add_f32_e32 v34, v34, v35
	ds_write_b32 v87, v34 offset:8320
